# rwkv_post_rows loop software-pipelined: next row's 5 loads prefetched into spare registers at loop top (counted vmcnt)
# baseline (speedup 1.0000x reference)
; #define GAS __attribute__((address_space(1)))
; __device__ __forceinline__ int mk_tid(int wid_s) { int t = wid_s * 64 + (int)__builtin_amdgcn_mbcnt_hi(~0u, __builtin_amdgcn_mbcnt_lo(~0u, 0u)); asm volatile("" : "+v"(t)); return t; }
; __device__ __forceinline__ void rwkv_post_rows(int wid_s, KP p_, int l, int r, int dummy) {
;     KP p = p_; asm volatile("" : "+s"(p));
;     unsigned char* ws = p->ws;
;     const int tid_ = mk_tid(wid_s);
;     const int tid = tid_, lane = tid & 63, wv = tid >> 6, c0 = lane * 8, h = lane >> 3;
;     const GAS bf16* P = (const GAS bf16*)(ws + R_P); const GAS bf16* SI = (const GAS bf16*)(ws + R_SI); GAS bf16* Y = (GAS bf16*)(ws + WS_Y) + (size_t)r * TH * 1536;
;     float rkc[8], lng[8], lnb[8];
;     ld8f((const GAS float*)p->in[I_RK] + l * 512 + c0, rkc); ld8f((const GAS float*)p->in[I_LNG] + l * 512 + c0, lng); ld8f((const GAS float*)p->in[I_LNB] + l * 512 + c0, lnb);
;     for (int row = blockIdx.x * 8 + wv; row < TH; row += gridDim.x * 8) {
;         const GAS bf16* si = SI + ((size_t)((row >> 11) * 8 + h) * 2048 + (row & 2047)) * 384 + (lane & 7) * 8;
;         const u32x4 rw = *(const GAS u32x4*)si, kw = *(const GAS u32x4*)(si + 128), vw = *(const GAS u32x4*)(si + 320);
;         const u32x4 gw = *(const GAS u32x4*)(P + (size_t)row * NP + c0);
;         GAS bf16* yp = Y + (size_t)row * 1536 + c0;
;         const u32x4 yw = *(const GAS u32x4*)yp;
.LBB0_1500:
	v_readlane_b32 s10, v254, 0
	v_readlane_b32 s11, v254, 1
	v_mov_b32_e32 v26, v169
	v_readlane_b32 s2, v254, 43
	v_ashrrev_i32_e32 v0, 6, v26
	v_readlane_b32 s3, v254, 44
	v_add_u32_e32 v42, s2, v0
	s_movk_i32 s2, 0x2000
	v_cmp_gt_i32_e32 vcc, s2, v42
	s_and_saveexec_b64 s[8:9], vcc
	s_movk_i32 s13, 0xc00
	s_movk_i32 s16, 0x1fff
	s_mov_b32 s17, 0x800000
	s_movk_i32 s18, 0x1a00
	s_movk_i32 s19, 0x7ff
	s_cbranch_execz .LBB0_1499
	s_load_dwordx2 s[2:3], s[10:11], 0x160
	v_readlane_b32 s4, v255, 6
	v_and_b32_e32 v2, 63, v26
	v_readlane_b32 s5, v255, 4
	v_lshlrev_b32_e32 v144, 4, v2
	s_waitcnt lgkmcnt(0)
	s_add_u32 s4, s2, s4
	s_addc_u32 s5, s3, s5
	v_lshl_add_u64 v[0:1], s[4:5], 0, v[144:145]
	s_mov_b64 s[4:5], 0x4a00000
	v_lshl_add_u64 v[24:25], v[0:1], 0, s[4:5]
	s_load_dwordx4 s[4:7], s[10:11], 0x88
	s_nop 0
	s_load_dwordx2 s[10:11], s[10:11], 0x98
	v_readlane_b32 s14, v255, 10
	v_readlane_b32 s15, v255, 11
	s_lshl_b64 s[14:15], s[14:15], 2
	v_lshlrev_b32_e32 v20, 5, v2
	s_waitcnt lgkmcnt(0)
	s_add_u32 s10, s10, s14
	s_addc_u32 s11, s11, s15
	s_add_u32 s6, s6, s14
	s_addc_u32 s7, s7, s15
	s_add_u32 s4, s4, s14
	s_addc_u32 s5, s5, s15
	global_load_dwordx4 v[0:3], v20, s[10:11]
	global_load_dwordx4 v[4:7], v20, s[10:11] offset:16
	global_load_dwordx4 v[8:11], v20, s[6:7]
	global_load_dwordx4 v[12:15], v20, s[6:7] offset:16
	global_load_dwordx4 v[16:19], v20, s[4:5]
	s_nop 0
	global_load_dwordx4 v[20:23], v20, s[4:5] offset:16
	v_bfe_u32 v43, v26, 3, 3
	v_lshlrev_b32_e32 v26, 4, v26
	v_and_b32_e32 v26, 0x70, v26
	v_mov_b32_e32 v27, v145
	v_lshl_add_u64 v[26:27], s[2:3], 0, v[26:27]
	s_mov_b64 s[4:5], 0xae00000
	v_lshl_add_u64 v[26:27], v[26:27], 0, s[4:5]
	s_load_dword s4, s[54:55], 0x0
	s_cmp_eq_u32 s12, 0
	v_lshl_add_u64 v[28:29], s[2:3], 0, v[144:145]
	s_mov_b64 s[2:3], 0x7a00000
	s_cselect_b64 vcc, -1, 0
	s_waitcnt lgkmcnt(0)
	s_lshl_b32 s6, s4, 3
	v_lshl_add_u64 v[28:29], v[28:29], 0, s[2:3]
	s_mov_b64 s[4:5], 0
	v_ashrrev_i32_e32 v70, 8, v42
	v_and_or_b32 v70, v70, -8, v43
	v_ashrrev_i32_e32 v71, 31, v70
	v_lshlrev_b64 v[70:71], 11, v[70:71]
	v_and_or_b32 v70, v42, s19, v70
	v_mad_u64_u32 v[72:73], s[2:3], v70, s33, v[26:27]
	v_mad_i32_i24 v73, v71, s33, v73
	global_load_dwordx4 v[74:77], v[72:73], off
	global_load_dwordx4 v[78:81], v[72:73], off offset:256
	global_load_dwordx4 v[82:85], v[72:73], off offset:640
	v_mad_i64_i32 v[70:71], s[2:3], v42, s18, v[28:29]
	v_mad_i64_i32 v[72:73], s[2:3], v42, s13, v[24:25]
	global_load_dwordx4 v[86:89], v[70:71], off
	global_load_dwordx4 v[90:93], v[72:73], off
	s_waitcnt vmcnt(0)
.LBB0_1502:
	s_waitcnt vmcnt(1)
	v_mad_i64_i32 v[30:31], s[2:3], v42, s18, v[28:29]
	v_mad_i64_i32 v[32:33], s[2:3], v42, s13, v[24:25]
	v_add_u32_e32 v42, s6, v42
	v_mov_b64_e32 v[34:35], v[74:75]
	v_mov_b64_e32 v[36:37], v[76:77]
	v_mov_b64_e32 v[38:39], v[78:79]
	v_mov_b64_e32 v[40:41], v[80:81]
	v_mov_b64_e32 v[44:45], v[82:83]
	v_mov_b64_e32 v[46:47], v[84:85]
	v_mov_b64_e32 v[48:49], v[86:87]
	v_mov_b64_e32 v[50:51], v[88:89]
	v_mov_b64_e32 v[52:53], v[90:91]
	v_mov_b64_e32 v[54:55], v[92:93]
	v_readfirstlane_b32 s2, v42
	s_cmp_gt_i32 s2, s16
	s_cbranch_scc1 .Lmy_post_nopf
	v_ashrrev_i32_e32 v70, 8, v42
	v_and_or_b32 v70, v70, -8, v43
	v_ashrrev_i32_e32 v71, 31, v70
	v_lshlrev_b64 v[70:71], 11, v[70:71]
	v_and_or_b32 v70, v42, s19, v70
	v_mad_u64_u32 v[72:73], s[2:3], v70, s33, v[26:27]
	v_mad_i32_i24 v73, v71, s33, v73
	global_load_dwordx4 v[74:77], v[72:73], off
	global_load_dwordx4 v[78:81], v[72:73], off offset:256
	global_load_dwordx4 v[82:85], v[72:73], off offset:640
	v_mad_i64_i32 v[70:71], s[2:3], v42, s18, v[28:29]
	v_mad_i64_i32 v[72:73], s[2:3], v42, s13, v[24:25]
	global_load_dwordx4 v[86:89], v[70:71], off
	global_load_dwordx4 v[90:93], v[72:73], off
; #define GAS __attribute__((address_space(1)))
; __device__ __forceinline__ float allreduce8(float x) { x += dppf<0xB1>(x); x += dppf<0x4E>(x); x += dppf<0x141>(x); return x; }
; __device__ __forceinline__ void unpack8(const u32x4 w, float* f) { f[0] = bflo(w.x); f[1] = bfhi(w.x); f[2] = bflo(w.y); f[3] = bfhi(w.y); f[4] = bflo(w.z); f[5] = bfhi(w.z); f[6] = bflo(w.w); f[7] = bfhi(w.w); }
; __device__ __forceinline__ u32x4 pack8(const float* f) { u32x4 o; o.x = pk2(f[0], f[1]); o.y = pk2(f[2], f[3]); o.z = pk2(f[4], f[5]); o.w = pk2(f[6], f[7]); return o; }
; __device__ __forceinline__ void rwkv_post_rows(int wid_s, KP p_, int l, int r, int dummy) {
;     ...
;         float rr[8], k2[8], vv[8], gg[8], y[8];
;         unpack8(rw, rr); unpack8(kw, k2); unpack8(vw, vv); unpack8(gw, gg); unpack8(yw, y);
;         float sy = 0.f, sb = 0.f;
; #pragma unroll
;         for (int e = 0; e < 8; ++e) { sy += y[e]; sb += rr[e] * k2[e] * rkc[e]; }
;         const float mean = allreduce8(sy) * (1.f / 64.f); const float bonus = allreduce8(sb);
;         float sv = 0.f;
; #pragma unroll
;         for (int e = 0; e < 8; ++e) { y[e] -= mean; sv += y[e] * y[e]; }
;         const float rs = rsqrtf(allreduce8(sv) * (1.f / 64.f) + 64e-5f);
; #pragma unroll
;         for (int e = 0; e < 8; ++e) y[e] = (y[e] * rs * lng[e] + lnb[e] + bonus * vv[e]) * gg[e];
;         if (dummy) yp = (GAS bf16*)(ws + R_P) + (size_t)row * NP + 600 + c0;
;         *(GAS u32x4*)yp = pack8(y);
;     }
.Lmy_post_nopf:
	v_and_b32_e32 v57, 0xffff0000, v34
	v_lshlrev_b32_e32 v56, 16, v34
	v_and_b32_e32 v59, 0xffff0000, v38
	v_lshlrev_b32_e32 v58, 16, v38
	v_pk_mul_f32 v[56:57], v[56:57], v[58:59]
	v_lshlrev_b32_e32 v62, 16, v44
	v_pk_mul_f32 v[56:57], v[16:17], v[56:57]
	v_lshlrev_b32_e32 v58, 16, v51
	v_add_f32_e32 v34, 0, v56
	v_add_f32_e32 v38, v57, v34
	v_and_b32_e32 v57, 0xffff0000, v35
	v_lshlrev_b32_e32 v56, 16, v35
	v_and_b32_e32 v35, 0xffff0000, v39
	v_lshlrev_b32_e32 v34, 16, v39
	v_pk_mul_f32 v[34:35], v[56:57], v[34:35]
	v_and_b32_e32 v39, 0xffff0000, v40
	v_pk_mul_f32 v[34:35], v[18:19], v[34:35]
	v_and_b32_e32 v57, 0xffff0000, v47
	v_add_f32_e32 v34, v34, v38
	v_add_f32_e32 v56, v35, v34
	v_and_b32_e32 v35, 0xffff0000, v36
	v_lshlrev_b32_e32 v34, 16, v36
	v_lshlrev_b32_e32 v38, 16, v40
	v_pk_mul_f32 v[34:35], v[34:35], v[38:39]
	v_lshlrev_b32_e32 v36, 16, v41
	v_pk_mul_f32 v[34:35], v[20:21], v[34:35]
	v_and_b32_e32 v59, 0xffff0000, v51
	v_add_f32_e32 v34, v34, v56
	v_add_f32_e32 v38, v35, v34
	v_and_b32_e32 v35, 0xffff0000, v37
	v_lshlrev_b32_e32 v34, 16, v37
	v_and_b32_e32 v37, 0xffff0000, v41
	v_pk_mul_f32 v[34:35], v[34:35], v[36:37]
	v_lshlrev_b32_e32 v56, 16, v47
	v_pk_mul_f32 v[34:35], v[22:23], v[34:35]
	v_and_b32_e32 v39, 0xffff0000, v46
	v_add_f32_e32 v34, v34, v38
	v_add_f32_e32 v34, v35, v34
	v_lshlrev_b32_e32 v38, 16, v46
	v_lshlrev_b32_e32 v46, 16, v50
	v_add_f32_dpp v34, v34, v34 quad_perm:[1,0,3,2] row_mask:0xf bank_mask:0xf bound_ctrl:1
	v_and_b32_e32 v47, 0xffff0000, v50
	v_lshlrev_b32_e32 v50, 16, v45
	v_add_f32_dpp v34, v34, v34 quad_perm:[2,3,0,1] row_mask:0xf bank_mask:0xf bound_ctrl:1
	v_and_b32_e32 v51, 0xffff0000, v45
	v_and_b32_e32 v63, 0xffff0000, v44
	v_lshlrev_b32_e32 v44, 16, v48
	v_and_b32_e32 v45, 0xffff0000, v48
	v_lshlrev_b32_e32 v48, 16, v52
	v_add_f32_dpp v40, v34, v34 row_half_mirror row_mask:0xf bank_mask:0xf bound_ctrl:1
	v_lshlrev_b32_e32 v34, 16, v55
	v_and_b32_e32 v35, 0xffff0000, v55
	v_lshlrev_b32_e32 v36, 16, v54
	v_and_b32_e32 v37, 0xffff0000, v54
	v_lshlrev_b32_e32 v54, 16, v49
	v_and_b32_e32 v55, 0xffff0000, v49
	v_and_b32_e32 v49, 0xffff0000, v52
	v_add_f32_e32 v41, 0, v48
	v_lshlrev_b32_e32 v60, 16, v53
	v_add_f32_e32 v41, v41, v49
	v_and_b32_e32 v61, 0xffff0000, v53
	v_add_f32_e32 v41, v41, v60
	v_add_f32_e32 v41, v41, v61
	v_add_f32_e32 v41, v41, v36
	v_add_f32_e32 v41, v41, v37
	v_add_f32_e32 v41, v41, v34
	v_add_f32_e32 v41, v41, v35
	s_nop 1
	v_add_f32_dpp v41, v41, v41 quad_perm:[1,0,3,2] row_mask:0xf bank_mask:0xf bound_ctrl:1
	s_nop 1
	v_add_f32_dpp v41, v41, v41 quad_perm:[2,3,0,1] row_mask:0xf bank_mask:0xf bound_ctrl:1
	s_nop 1
	v_add_f32_dpp v41, v41, v41 row_half_mirror row_mask:0xf bank_mask:0xf bound_ctrl:1
	v_mul_f32_e32 v52, 0x3c800000, v41
	v_pk_add_f32 v[48:49], v[48:49], v[52:53] op_sel_hi:[1,0] neg_lo:[0,1] neg_hi:[0,1]
	v_pk_add_f32 v[60:61], v[60:61], v[52:53] op_sel_hi:[1,0] neg_lo:[0,1] neg_hi:[0,1]
	v_pk_mul_f32 v[64:65], v[48:49], v[48:49]
	v_pk_mul_f32 v[66:67], v[60:61], v[60:61]
	v_add_f32_e32 v41, v64, v65
	v_pk_add_f32 v[68:69], v[36:37], v[52:53] op_sel_hi:[1,0] neg_lo:[0,1] neg_hi:[0,1]
	v_add_f32_e32 v41, v66, v41
	v_pk_mul_f32 v[36:37], v[68:69], v[68:69]
	v_add_f32_e32 v41, v67, v41
	v_pk_add_f32 v[52:53], v[34:35], v[52:53] op_sel_hi:[1,0] neg_lo:[0,1] neg_hi:[0,1]
	v_add_f32_e32 v36, v36, v41
	v_pk_mul_f32 v[34:35], v[52:53], v[52:53]
	v_add_f32_e32 v36, v37, v36
	v_add_f32_e32 v34, v34, v36
	v_add_f32_e32 v34, v35, v34
	v_mov_b32_e32 v35, 0x3a27c5ac
	s_nop 0
	v_add_f32_dpp v34, v34, v34 quad_perm:[1,0,3,2] row_mask:0xf bank_mask:0xf bound_ctrl:1
	s_nop 1
	v_add_f32_dpp v34, v34, v34 quad_perm:[2,3,0,1] row_mask:0xf bank_mask:0xf bound_ctrl:1
	s_nop 1
	v_add_f32_dpp v34, v34, v34 row_half_mirror row_mask:0xf bank_mask:0xf bound_ctrl:1
	v_fmamk_f32 v34, v34, 0x3c800000, v35
	v_cmp_gt_f32_e64 s[2:3], s17, v34
	v_mul_f32_e32 v35, 0x4b800000, v34
	s_nop 0
	v_cndmask_b32_e64 v34, v34, v35, s[2:3]
	v_rsq_f32_e32 v34, v34
	s_nop 0
	v_mul_f32_e32 v35, 0x45800000, v34
	v_cndmask_b32_e64 v64, v34, v35, s[2:3]
	v_pk_mul_f32 v[34:35], v[48:49], v[64:65] op_sel_hi:[1,0]
	v_pk_mul_f32 v[36:37], v[60:61], v[64:65] op_sel_hi:[1,0]
	v_pk_fma_f32 v[34:35], v[8:9], v[34:35], v[0:1]
	v_pk_fma_f32 v[36:37], v[10:11], v[36:37], v[2:3]
	v_pk_fma_f32 v[34:35], v[40:41], v[62:63], v[34:35] op_sel_hi:[0,1,1]
	v_pk_mul_f32 v[34:35], v[34:35], v[44:45]
	v_pk_mul_f32 v[44:45], v[68:69], v[64:65] op_sel_hi:[1,0]
	v_pk_fma_f32 v[36:37], v[40:41], v[50:51], v[36:37] op_sel_hi:[0,1,1]
	v_pk_fma_f32 v[44:45], v[12:13], v[44:45], v[4:5]
	s_mov_b64 s[2:3], 0x4b0
	v_pk_fma_f32 v[38:39], v[40:41], v[38:39], v[44:45] op_sel_hi:[0,1,1]
	v_pk_mul_f32 v[44:45], v[52:53], v[64:65] op_sel_hi:[1,0]
	v_pk_mul_f32 v[36:37], v[36:37], v[54:55]
	v_pk_fma_f32 v[44:45], v[14:15], v[44:45], v[6:7]
	v_pk_mul_f32 v[38:39], v[38:39], v[46:47]
	v_pk_fma_f32 v[40:41], v[40:41], v[56:57], v[44:45] op_sel_hi:[0,1,1]
	v_pk_mul_f32 v[40:41], v[40:41], v[58:59]
	v_lshl_add_u64 v[30:31], v[30:31], 0, s[2:3]
	v_cmp_lt_i32_e64 s[2:3], s16, v42
	v_cndmask_b32_e32 v45, v31, v33, vcc
	v_cndmask_b32_e32 v44, v30, v32, vcc
	v_cvt_pk_bf16_f32 v30, v34, v35
	v_cvt_pk_bf16_f32 v31, v36, v37
	v_cvt_pk_bf16_f32 v32, v38, v39
	v_cvt_pk_bf16_f32 v33, v40, v41
	s_or_b64 s[4:5], s[2:3], s[4:5]
	global_store_dwordx4 v[44:45], v[30:33], off
	s_andn2_b64 exec, exec, s[4:5]
	s_cbranch_execnz .LBB0_1502
	s_branch .LBB0_1499
